# stick-breaking task: lane-xor-32 exchanges done with v_permlane32_swap plus a select instead of ds_bpermute round trips
# speedup vs baseline: 1.0035x; 1.0006x over previous
; __device__ __forceinline__ void sb_task(ATT_LAS unsigned char* wl  , int b, int h, int qb, const bf16_t* __restrict__ SQ, const bf16_t* __restrict__ SK, const bf16_t* __restrict__ VT, const float* __restrict__ gout, bf16_t* __restrict__ MIXED) {
;     const int lane = threadIdx.x & 63, r = lane & 31, hh = lane >> 5, t0 = 32 * qb;
;     bf16x8 qf[8];
; #pragma unroll
;     for (int s = 0; s < 8; ++s) qf[s] = *(const bf16x8*)(SQ + (size_t)(b * 4096 + t0 + r) * 1024 + h * 128 + 16 * s + 8 * hh);
;     f32x16 O[4];
; #pragma unroll
;     for (int e = 0; e < 4; ++e)
; #pragma unroll
;         for (int i = 0; i < 16; ++i) O[e][i] = 0.f;
;     float carry = 0.f;
;     const bf16_t* kbase = SK + (size_t)(b * 8 + h) * 130 * 4096 + lane * 8;
;     const bf16_t* vbase = VT + (size_t)1024 * KTOT + (size_t)(b * 8 + h) * 130 * 4096 + lane * 8;
;     ...
;         bf16x8 kf[8];
; #pragma unroll
;         for (int s = 0; s < 8; ++s) kf[s] = *(const bf16x8*)(kbase + (size_t)jt * 4096 + 512 * s);
;         bf16x8 vf[2][4];
; #pragma unroll
;         for (int s2 = 0; s2 < 2; ++s2)
; #pragma unroll
;             for (int e = 0; e < 4; ++e) vf[s2][e] = *(const bf16x8*)(vbase + (size_t)jt * 4096 + (s2 * 4 + e) * 512);
;         f32x16 S;
; #pragma unroll
;         for (int i = 0; i < 16; ++i) S[i] = 0.f;
; #pragma unroll
;         for (int s = 0; s < 8; ++s) S = __builtin_amdgcn_mfma_f32_32x32x16_bf16(kf[s], qf[s], S, 0, 0, 0);
;         const bool diag = (jt == 2 + qb), first = (jt == 1);
;         float L[16]; unsigned vm = 0u;
; #pragma unroll
;         for (int i = 0; i < 16; ++i) { const int kap = 16 * (i >> 3) + 8 * hh + (i & 7); const bool valid = !(diag && kap >= r) && !(first && kap < 16);
;             const float z = S[i], sp = fmaxf(z, 0.f) + __builtin_amdgcn_logf(1.0f + __builtin_amdgcn_exp2f(-fabsf(z)));
;             L[i] = valid ? -sp : 0.f; vm |= valid ? (1u << i) : 0u; }
.LBB0_560:
	s_mov_b32 s98, -1
	s_mov_b32 s99, 0
	s_lshl_b32 s58, s70, 3
	s_add_i32 s0, s58, s69
	s_cmpk_gt_i32 s0, 0xfff
	s_cbranch_scc1 .LBB0_567
	v_lshlrev_b32_e32 v0, 3, v157
	v_or_b32_e32 v7, 7, v0
	v_mov_b32_e32 v8, 0x80
	v_cmp_lt_u32_e64 s[18:19], v7, v188
	v_or_b32_e32 v176, 16, v0
	v_or_b32_e32 v9, 17, v0
	v_or_b32_e32 v2, 2, v0
	v_or_b32_e32 v4, 4, v0
	v_cndmask_b32_e64 v7, 0, v8, s[18:19]
	v_mov_b32_e32 v8, 0x100
	v_cmp_lt_u32_e64 s[20:21], v176, v188
	v_mov_b32_e32 v10, 0x200
	v_cmp_lt_u32_e64 s[22:23], v9, v188
	v_or_b32_e32 v1, 1, v0
	v_cmp_lt_u32_e64 s[8:9], v2, v188
	v_or_b32_e32 v3, 3, v0
	v_cmp_lt_u32_e64 s[12:13], v4, v188
	v_cndmask_b32_e64 v8, 0, v8, s[20:21]
	v_cndmask_b32_e64 v9, 0, v10, s[22:23]
	v_cmp_lt_u32_e64 s[6:7], v1, v188
	v_cndmask_b32_e64 v2, 0, 4, s[8:9]
	v_cmp_lt_u32_e64 s[10:11], v3, v188
	v_cndmask_b32_e64 v4, 0, 16, s[12:13]
	v_or3_b32 v7, v7, v9, v8
	v_cndmask_b32_e64 v1, 0, 2, s[6:7]
	v_cndmask_b32_e64 v3, 0, 8, s[10:11]
	v_or3_b32 v2, v4, v2, v7
	v_or3_b32 v1, v3, v1, v2
	v_or_b32_e32 v2, 18, v0
	v_mov_b32_e32 v3, 0x400
	v_cmp_lt_u32_e64 s[24:25], v2, v188
	v_mov_b32_e32 v145, 0
	v_lshlrev_b32_e32 v144, 4, v154
	v_or_b32_e32 v5, 5, v0
	v_or_b32_e32 v6, 6, v0
	v_cndmask_b32_e64 v2, 0, v3, s[24:25]
	v_or_b32_e32 v3, 19, v0
	v_lshl_add_u64 v[146:147], s[16:17], 0, v[144:145]
	v_cmp_lt_u32_e64 s[14:15], v5, v188
	v_cmp_lt_u32_e64 s[16:17], v6, v188
	v_mov_b32_e32 v4, 0x800
	v_cmp_lt_u32_e64 s[26:27], v3, v188
	v_cndmask_b32_e64 v5, 0, 32, s[14:15]
	v_cndmask_b32_e64 v6, 0, 64, s[16:17]
	v_cndmask_b32_e64 v3, 0, v4, s[26:27]
	v_or_b32_e32 v4, 20, v0
	v_or3_b32 v1, v5, v6, v1
	v_mov_b32_e32 v5, 0x1000
	v_cmp_lt_u32_e64 s[28:29], v4, v188
	v_mov_b32_e32 v6, 0x2000
	v_mov_b32_e32 v7, 0x4000
	v_cndmask_b32_e64 v4, 0, v5, s[28:29]
	v_or_b32_e32 v5, 21, v0
	v_cmp_lt_u32_e64 s[30:31], v5, v188
	v_or_b32_e32 v2, v2, v3
	v_mov_b32_e32 v8, 0x8000
	v_cndmask_b32_e64 v5, 0, v6, s[30:31]
	v_or_b32_e32 v6, 22, v0
	v_cmp_lt_u32_e64 s[34:35], v6, v188
	v_or_b32_e32 v3, v2, v1
	v_or_b32_e32 v4, v4, v5
	v_cndmask_b32_e64 v6, 0, v7, s[34:35]
	v_or_b32_e32 v7, 23, v0
	v_cmp_lt_u32_e64 s[36:37], v7, v188
	s_lshl_b32 s1, s69, 14
	v_or_b32_e32 v5, v4, v3
	v_cndmask_b32_e64 v7, 0, v8, s[36:37]
	s_movk_i32 s40, 0x4000
	s_mov_b32 s38, 0x8000
	v_or_b32_e32 v6, v6, v7
	s_add_i32 s60, s1, 0
	s_movk_i32 s1, 0x1000
	s_movk_i32 s42, 0x2000
	v_bitop3_b32 v7, v6, s38, v5 bitop3:0xc8
	v_bitop3_b32 v5, v6, s40, v5 bitop3:0xc8
	s_movk_i32 s48, 0x400
	s_movk_i32 s46, 0x800
	v_cmp_eq_u32_e64 s[40:41], 0, v5
	v_bitop3_b32 v5, v4, s42, v3 bitop3:0xc8
	v_bitop3_b32 v3, v4, s1, v3 bitop3:0xc8
	v_cmp_eq_u32_e64 s[44:45], 0, v3
	v_bitop3_b32 v3, v2, s46, v1 bitop3:0xc8
	v_bitop3_b32 v1, v2, s48, v1 bitop3:0xc8
	v_writelane_b32 v238, s68, 19
	v_cmp_eq_u32_e64 s[48:49], 0, v1
	s_movk_i32 s61, 0x110
	v_mov_b32_e32 v1, s60
	v_mad_u32_u24 v177, v188, s61, v1
	s_mov_b32 s61, s69
	v_readlane_b32 s64, v238, 2
	v_lshl_add_u64 v[148:149], s[86:87], 0, v[144:145]
	v_lshlrev_b32_e32 v144, 4, v157
	v_readlane_b32 s70, v238, 8
	v_readlane_b32 s71, v238, 9
	v_and_b32_e32 v2, 15, v186
	v_lshlrev_b32_e32 v4, 11, v155
	s_mov_b64 s[4:5], 0x183e1000
	v_cmp_eq_u32_e64 s[38:39], 0, v7
	v_cmp_eq_u32_e64 s[42:43], 0, v5
	v_cmp_eq_u32_e64 s[46:47], 0, v3
	v_readlane_b32 s72, v238, 10
	v_readlane_b32 s75, v238, 13
	v_lshl_add_u64 v[152:153], s[70:71], 0, v[144:145]
	v_or_b32_e32 v1, 32, v0
	v_or_b32_e32 v3, 48, v0
	v_or_b32_e32 v5, 64, v0
	v_or_b32_e32 v7, 0x50, v0
	v_or_b32_e32 v9, 0x60, v0
	v_or_b32_e32 v11, 0x70, v0
	v_or_b32_e32 v13, 0x80, v0
	v_or_b32_e32 v15, 0x90, v0
	v_or_b32_e32 v17, 0xa0, v0
	v_or_b32_e32 v19, 0xb0, v0
	v_or_b32_e32 v20, 0xc0, v0
	v_or_b32_e32 v21, 0xd0, v0
	v_or_b32_e32 v22, 0xe0, v0
	v_or_b32_e32 v23, 0xf0, v0
	v_lshl_add_u32 v24, v2, 4, s60
	v_lshlrev_b32_e32 v2, 3, v2
	v_mul_u32_u24_e32 v25, 0x110, v155
	v_or_b32_e32 v6, 0x2000, v4
	v_or_b32_e32 v8, 0x4000, v4
	v_or_b32_e32 v10, 0x6000, v4
	v_or_b32_e32 v12, 0x8000, v4
	v_or_b32_e32 v14, 0xa000, v4
	v_or_b32_e32 v16, 0xc000, v4
	v_or_b32_e32 v18, 0xe000, v4
	s_add_i32 s71, s58, s61
	s_movk_i32 s60, 0xe000
	s_mov_b32 s59, 0
	v_lshl_add_u64 v[150:151], v[148:149], 0, s[4:5]
	v_cmp_gt_u32_e64 s[50:51], 32, v154
	v_cmp_lt_u32_e64 s[4:5], v0, v188
	s_lshl_b32 s70, s3, 3
	s_mov_b32 s72, 0xc3200000
	s_mov_b32 s61, -1
	v_mov_b32_e32 v178, 0x358637bd
	s_mov_b32 s75, 0x800000
	v_add_u32_e32 v179, v177, v0
	v_add_u32_e32 v180, v177, v1
	v_add_u32_e32 v181, v177, v3
	v_add_u32_e32 v182, v177, v5
	v_add_u32_e32 v183, v177, v7
	v_add_u32_e32 v184, v177, v9
	v_add_u32_e32 v185, v177, v11
	v_add_u32_e32 v189, v177, v13
	v_add_u32_e32 v190, v177, v15
	v_add_u32_e32 v191, v177, v17
	v_add_u32_e32 v192, v177, v19
	v_add_u32_e32 v193, v177, v20
	v_add_u32_e32 v194, v177, v21
	v_add_u32_e32 v195, v177, v22
	v_add_u32_e32 v196, v177, v23
	v_lshlrev_b32_e32 v154, 1, v2
	v_add_u32_e32 v197, v24, v25
	v_lshlrev_b32_e32 v156, 1, v4
	v_lshlrev_b32_e32 v158, 1, v6
	v_lshlrev_b32_e32 v160, 1, v8
	v_lshlrev_b32_e32 v162, 1, v10
	v_lshlrev_b32_e32 v164, 1, v12
	v_lshlrev_b32_e32 v166, 1, v14
	v_lshlrev_b32_e32 v168, 1, v16
	v_lshlrev_b32_e32 v170, 1, v18
	v_lshlrev_b32_e32 v172, 1, v0
	v_mov_b32_e32 v173, v145
	v_mov_b32_e32 v198, 0x104000
	v_readlane_b32 s65, v238, 3
	v_readlane_b32 s66, v238, 4
	v_readlane_b32 s67, v238, 5
	v_readlane_b32 s68, v238, 6
	v_readlane_b32 s69, v238, 7
	v_readlane_b32 s73, v238, 11
	v_readlane_b32 s74, v238, 12
	v_readlane_b32 s76, v238, 14
	v_readlane_b32 s77, v238, 15
	v_readlane_b32 s78, v238, 16
	v_readlane_b32 s79, v238, 17
	s_branch .LBB0_563
; __device__ __forceinline__ unsigned cvt_pk_bf16(float lo, float hi) { unsigned r; asm volatile("v_cvt_pk_bf16_f32 %0, %1, %2" : "=v"(r) : "v"(lo), "v"(hi)); return r; }
; #define ATT_LAS __attribute__((address_space(3)))
; __device__ __forceinline__ void sb_task(ATT_LAS unsigned char* wl  , int b, int h, int qb, const bf16_t* __restrict__ SQ, const bf16_t* __restrict__ SK, const bf16_t* __restrict__ VT, const float* __restrict__ gout, bf16_t* __restrict__ MIXED) {
;     ...
;     float ss = 0.f;
; #pragma unroll
;     for (int e = 0; e < 4; ++e)
; #pragma unroll
;         for (int i = 0; i < 16; ++i) ss += O[e][i] * O[e][i];
;     ss += __shfl_xor(ss, 32);
;     const float rstd = rsqrtf(ss * (1.0f / 128.0f) + EPS);
; #pragma unroll
;     for (int e = 0; e < 4; ++e)
; #pragma unroll
;         for (int g4 = 0; g4 < 4; ++g4) { const int e0 = 32 * e + 8 * g4 + 4 * hh; const f32x4 g = *(const f32x4*)(gout + e0);
;             u32x2 w; w.x = cvt_pk_bf16(O[e][4 * g4] * rstd * g[0], O[e][4 * g4 + 1] * rstd * g[1]); w.y = cvt_pk_bf16(O[e][4 * g4 + 2] * rstd * g[2], O[e][4 * g4 + 3] * rstd * g[3]);
;             *(ATT_LAS u32x2*)(wl + r * OSTG_PITCH + e0 * 2) = w; }
.LBB0_562:
	s_nop 2
	v_mul_f32_e32 v78, v49, v49
	global_load_dwordx4 v[80:83], v[152:153], off
	global_load_dwordx4 v[84:87], v[152:153], off offset:32
	global_load_dwordx4 v[88:91], v[152:153], off offset:64
	global_load_dwordx4 v[92:95], v[152:153], off offset:96
	global_load_dwordx4 v[96:99], v[152:153], off offset:128
	global_load_dwordx4 v[100:103], v[152:153], off offset:160
	global_load_dwordx4 v[104:107], v[152:153], off offset:192
	global_load_dwordx4 v[108:111], v[152:153], off offset:224
	global_load_dwordx4 v[112:115], v[152:153], off offset:256
	global_load_dwordx4 v[116:119], v[152:153], off offset:288
	global_load_dwordx4 v[120:123], v[152:153], off offset:320
	global_load_dwordx4 v[124:127], v[152:153], off offset:352
	global_load_dwordx4 v[128:131], v[152:153], off offset:384
	global_load_dwordx4 v[132:135], v[152:153], off offset:416
	global_load_dwordx4 v[136:139], v[152:153], off offset:448
	global_load_dwordx4 v[140:143], v[152:153], off offset:480
	v_fmac_f32_e32 v78, v48, v48
	v_fmac_f32_e32 v78, v50, v50
	v_fmac_f32_e32 v78, v51, v51
	v_fmac_f32_e32 v78, v52, v52
	v_fmac_f32_e32 v78, v53, v53
	v_fmac_f32_e32 v78, v54, v54
	v_fmac_f32_e32 v78, v55, v55
	v_fmac_f32_e32 v78, v56, v56
	v_fmac_f32_e32 v78, v57, v57
	v_fmac_f32_e32 v78, v58, v58
	v_fmac_f32_e32 v78, v59, v59
	v_fmac_f32_e32 v78, v60, v60
	v_fmac_f32_e32 v78, v61, v61
	v_fmac_f32_e32 v78, v62, v62
	v_fmac_f32_e32 v78, v63, v63
	v_fmac_f32_e32 v78, v32, v32
	v_fmac_f32_e32 v78, v33, v33
	v_fmac_f32_e32 v78, v34, v34
	v_fmac_f32_e32 v78, v35, v35
	v_fmac_f32_e32 v78, v36, v36
	v_fmac_f32_e32 v78, v37, v37
	v_fmac_f32_e32 v78, v38, v38
	v_fmac_f32_e32 v78, v39, v39
	v_fmac_f32_e32 v78, v40, v40
	v_fmac_f32_e32 v78, v41, v41
	v_fmac_f32_e32 v78, v42, v42
	v_fmac_f32_e32 v78, v43, v43
	v_fmac_f32_e32 v78, v44, v44
	v_fmac_f32_e32 v78, v45, v45
	v_fmac_f32_e32 v78, v46, v46
	v_fmac_f32_e32 v78, v47, v47
	v_fmac_f32_e32 v78, v16, v16
	v_fmac_f32_e32 v78, v17, v17
	v_fmac_f32_e32 v78, v18, v18
	v_fmac_f32_e32 v78, v19, v19
	v_fmac_f32_e32 v78, v20, v20
	v_fmac_f32_e32 v78, v21, v21
	v_fmac_f32_e32 v78, v22, v22
	v_fmac_f32_e32 v78, v23, v23
	v_fmac_f32_e32 v78, v24, v24
	v_fmac_f32_e32 v78, v25, v25
	v_fmac_f32_e32 v78, v26, v26
	v_fmac_f32_e32 v78, v27, v27
	v_fmac_f32_e32 v78, v28, v28
	v_fmac_f32_e32 v78, v29, v29
	v_fmac_f32_e32 v78, v30, v30
	v_fmac_f32_e32 v78, v31, v31
	v_fmac_f32_e32 v78, v0, v0
	v_fmac_f32_e32 v78, v1, v1
	v_fmac_f32_e32 v78, v2, v2
	v_fmac_f32_e32 v78, v3, v3
	v_fmac_f32_e32 v78, v4, v4
	v_fmac_f32_e32 v78, v5, v5
	v_pk_mul_f32 v[76:77], v[6:7], v[6:7]
	v_pk_mul_f32 v[74:75], v[8:9], v[8:9]
	v_add_f32_e32 v76, v76, v78
	v_add_f32_e32 v76, v77, v76
	v_add_f32_e32 v74, v74, v76
	v_pk_mul_f32 v[72:73], v[10:11], v[10:11]
	v_add_f32_e32 v74, v75, v74
	v_add_f32_e32 v72, v72, v74
	v_pk_mul_f32 v[70:71], v[12:13], v[12:13]
	v_add_f32_e32 v72, v73, v72
	v_add_f32_e32 v70, v70, v72
	v_pk_mul_f32 v[68:69], v[14:15], v[14:15]
	v_add_f32_e32 v70, v71, v70
	v_add_f32_e32 v68, v68, v70
	v_add_f32_e32 v68, v69, v68
	v_mov_b32_e32 v69, v68
	v_mov_b32_e32 v225, v68
	s_nop 1
	v_permlane32_swap_b32_e32 v69, v225
	v_cndmask_b32_e64 v69, v69, v225, s[98:99]
	s_lshl_b32 s58, s63, 7
	s_ashr_i32 s63, s62, 31
	s_lshl_b64 s[62:63], s[62:63], 12
	s_add_u32 s62, s90, s62
	s_waitcnt lgkmcnt(0)
	v_add_f32_e32 v68, v68, v69
	v_fmamk_f32 v68, v68, 0x3c000000, v178
	v_mul_f32_e32 v69, 0x4b800000, v68
	v_cmp_gt_f32_e32 vcc, s75, v68
	s_addc_u32 s63, s91, s63
	s_lshl_b32 s58, s58, 1
	v_cndmask_b32_e32 v68, v68, v69, vcc
	v_rsq_f32_e32 v68, v68
	s_add_u32 s62, s62, s58
	v_mov_b32_e32 v155, v145
	s_addc_u32 s63, s63, 0
	v_mul_f32_e32 v69, 0x45800000, v68
	v_cndmask_b32_e32 v68, v68, v69, vcc
	v_mul_f32_e32 v48, v48, v68
	v_mul_f32_e32 v49, v49, v68
	s_waitcnt vmcnt(0)
	v_mul_f32_e32 v48, v80, v48
	v_mul_f32_e32 v49, v81, v49
	v_cvt_pk_bf16_f32 v64, v48, v49
	v_mul_f32_e32 v48, v50, v68
	v_mul_f32_e32 v49, v51, v68
	v_mul_f32_e32 v48, v82, v48
	v_mul_f32_e32 v49, v83, v49
	v_cvt_pk_bf16_f32 v65, v48, v49
	v_mul_f32_e32 v52, v52, v68
	v_mul_f32_e32 v53, v53, v68
	v_mul_f32_e32 v54, v54, v68
	v_mul_f32_e32 v55, v55, v68
	ds_write_b64 v179, v[64:65]
	v_mul_f32_e32 v32, v32, v68
	v_mul_f32_e32 v33, v33, v68
	v_mul_f32_e32 v34, v34, v68
	v_mul_f32_e32 v35, v35, v68
	v_mul_f32_e32 v36, v36, v68
	v_mul_f32_e32 v37, v37, v68
	v_mul_f32_e32 v38, v38, v68
	v_mul_f32_e32 v39, v39, v68
	v_mul_f32_e32 v16, v16, v68
	v_mul_f32_e32 v17, v17, v68
	v_mul_f32_e32 v18, v18, v68
	v_mul_f32_e32 v19, v19, v68
	v_mul_f32_e32 v20, v20, v68
	v_mul_f32_e32 v21, v21, v68
	v_mul_f32_e32 v22, v22, v68
	v_mul_f32_e32 v23, v23, v68
	v_mul_f32_e32 v0, v0, v68
	v_mul_f32_e32 v1, v1, v68
	v_mul_f32_e32 v2, v2, v68
	v_mul_f32_e32 v3, v3, v68
	v_mul_f32_e32 v4, v4, v68
	v_mul_f32_e32 v5, v5, v68
	v_mul_f32_e32 v6, v6, v68
	v_mul_f32_e32 v7, v7, v68
	v_mov_b32_e32 v157, v145
	v_mov_b32_e32 v159, v145
	v_mov_b32_e32 v161, v145
	v_mov_b32_e32 v163, v145
	v_mov_b32_e32 v165, v145
	v_mov_b32_e32 v167, v145
	v_mov_b32_e32 v169, v145
	v_mov_b32_e32 v171, v145
	s_add_i32 s0, s0, s70
	s_add_i32 s71, s71, s70
	s_cmpk_lt_i32 s0, 0x1000
	v_mul_f32_e32 v48, v84, v52
	v_mul_f32_e32 v49, v85, v53
	v_mul_f32_e32 v50, v86, v54
	v_mul_f32_e32 v51, v87, v55
	v_cvt_pk_bf16_f32 v52, v48, v49
	v_cvt_pk_bf16_f32 v53, v50, v51
	v_mul_f32_e32 v55, v56, v68
	v_mul_f32_e32 v56, v57, v68
	v_mul_f32_e32 v57, v58, v68
	v_mul_f32_e32 v58, v59, v68
	v_add_u32_e32 v54, v177, v176
	ds_write_b64 v54, v[52:53]
	v_mul_f32_e32 v54, v60, v68
	v_mul_f32_e32 v48, v88, v55
	v_mul_f32_e32 v49, v89, v56
	v_mul_f32_e32 v50, v90, v57
; __device__ __forceinline__ unsigned cvt_pk_bf16(float lo, float hi) { unsigned r; asm volatile("v_cvt_pk_bf16_f32 %0, %1, %2" : "=v"(r) : "v"(lo), "v"(hi)); return r; }
; #define ATT_LAS __attribute__((address_space(3)))
; __device__ __forceinline__ void sb_task(ATT_LAS unsigned char* wl  , int b, int h, int qb, const bf16_t* __restrict__ SQ, const bf16_t* __restrict__ SK, const bf16_t* __restrict__ VT, const float* __restrict__ gout, bf16_t* __restrict__ MIXED) {
;     ...
;     for (int e = 0; e < 4; ++e)
; #pragma unroll
;         for (int g4 = 0; g4 < 4; ++g4) { const int e0 = 32 * e + 8 * g4 + 4 * hh; const f32x4 g = *(const f32x4*)(gout + e0);
;             u32x2 w; w.x = cvt_pk_bf16(O[e][4 * g4] * rstd * g[0], O[e][4 * g4 + 1] * rstd * g[1]); w.y = cvt_pk_bf16(O[e][4 * g4 + 2] * rstd * g[2], O[e][4 * g4 + 3] * rstd * g[3]);
;             *(ATT_LAS u32x2*)(wl + r * OSTG_PITCH + e0 * 2) = w; }
;     asm volatile("s_waitcnt lgkmcnt(0)" ::: "memory");
;     bf16_t* obase = MIXED + (size_t)(b * 4096 + t0) * 2048 + 1024 + h * 128;
; #pragma unroll
;     for (int i = 0; i < 8; ++i) { const int c = lane + 64 * i, row = c >> 4, c16 = c & 15;
;         *(u32x4*)(obase + (size_t)row * 2048 + c16 * 8) = *(const ATT_LAS u32x4*)(wl + row * OSTG_PITCH + c16 * 16); }
;     asm volatile("s_waitcnt lgkmcnt(0)" ::: "memory");
	v_mul_f32_e32 v51, v91, v58
	v_cvt_pk_bf16_f32 v52, v48, v49
	v_cvt_pk_bf16_f32 v53, v50, v51
	v_mul_f32_e32 v55, v61, v68
	v_mul_f32_e32 v56, v62, v68
	v_mul_f32_e32 v57, v63, v68
	ds_write_b64 v180, v[52:53]
	v_mul_f32_e32 v48, v92, v54
	v_mul_f32_e32 v49, v93, v55
	v_mul_f32_e32 v50, v94, v56
	v_mul_f32_e32 v51, v95, v57
	v_cvt_pk_bf16_f32 v52, v48, v49
	v_cvt_pk_bf16_f32 v53, v50, v51
	ds_write_b64 v181, v[52:53]
	v_mul_f32_e32 v32, v96, v32
	v_mul_f32_e32 v33, v97, v33
	v_mul_f32_e32 v34, v98, v34
	v_mul_f32_e32 v35, v99, v35
	v_cvt_pk_bf16_f32 v48, v32, v33
	v_cvt_pk_bf16_f32 v49, v34, v35
	ds_write_b64 v182, v[48:49]
	v_mul_f32_e32 v32, v100, v36
	v_mul_f32_e32 v33, v101, v37
	v_mul_f32_e32 v34, v102, v38
	v_mul_f32_e32 v35, v103, v39
	v_cvt_pk_bf16_f32 v36, v32, v33
	v_cvt_pk_bf16_f32 v37, v34, v35
	v_mul_f32_e32 v38, v40, v68
	v_mul_f32_e32 v39, v41, v68
	v_mul_f32_e32 v40, v42, v68
	v_mul_f32_e32 v41, v43, v68
	ds_write_b64 v183, v[36:37]
	v_mul_f32_e32 v32, v104, v38
	v_mul_f32_e32 v33, v105, v39
	v_mul_f32_e32 v34, v106, v40
	v_mul_f32_e32 v35, v107, v41
	v_cvt_pk_bf16_f32 v36, v32, v33
	v_cvt_pk_bf16_f32 v37, v34, v35
	v_mul_f32_e32 v38, v44, v68
	v_mul_f32_e32 v39, v45, v68
	v_mul_f32_e32 v40, v46, v68
	v_mul_f32_e32 v41, v47, v68
	ds_write_b64 v184, v[36:37]
	v_mul_f32_e32 v32, v108, v38
	v_mul_f32_e32 v33, v109, v39
	v_mul_f32_e32 v34, v110, v40
	v_mul_f32_e32 v35, v111, v41
	v_cvt_pk_bf16_f32 v36, v32, v33
	v_cvt_pk_bf16_f32 v37, v34, v35
	ds_write_b64 v185, v[36:37]
	v_mul_f32_e32 v16, v112, v16
	v_mul_f32_e32 v17, v113, v17
	v_mul_f32_e32 v18, v114, v18
	v_mul_f32_e32 v19, v115, v19
	v_cvt_pk_bf16_f32 v32, v16, v17
	v_cvt_pk_bf16_f32 v33, v18, v19
	ds_write_b64 v189, v[32:33]
	v_mul_f32_e32 v16, v116, v20
	v_mul_f32_e32 v17, v117, v21
	v_mul_f32_e32 v18, v118, v22
	v_mul_f32_e32 v19, v119, v23
	v_cvt_pk_bf16_f32 v20, v16, v17
	v_cvt_pk_bf16_f32 v21, v18, v19
	v_mul_f32_e32 v22, v24, v68
	v_mul_f32_e32 v23, v25, v68
	v_mul_f32_e32 v24, v26, v68
	v_mul_f32_e32 v25, v27, v68
	ds_write_b64 v190, v[20:21]
	v_mul_f32_e32 v16, v120, v22
	v_mul_f32_e32 v17, v121, v23
	v_mul_f32_e32 v18, v122, v24
	v_mul_f32_e32 v19, v123, v25
	v_cvt_pk_bf16_f32 v20, v16, v17
	v_cvt_pk_bf16_f32 v21, v18, v19
	v_mul_f32_e32 v22, v28, v68
	v_mul_f32_e32 v23, v29, v68
	v_mul_f32_e32 v24, v30, v68
	v_mul_f32_e32 v25, v31, v68
	ds_write_b64 v191, v[20:21]
	v_mul_f32_e32 v16, v124, v22
	v_mul_f32_e32 v17, v125, v23
	v_mul_f32_e32 v18, v126, v24
	v_mul_f32_e32 v19, v127, v25
	v_cvt_pk_bf16_f32 v20, v16, v17
	v_cvt_pk_bf16_f32 v21, v18, v19
	ds_write_b64 v192, v[20:21]
	v_mul_f32_e32 v0, v128, v0
	v_mul_f32_e32 v1, v129, v1
	v_mul_f32_e32 v2, v130, v2
	v_mul_f32_e32 v3, v131, v3
	v_cvt_pk_bf16_f32 v16, v0, v1
	v_cvt_pk_bf16_f32 v17, v2, v3
	ds_write_b64 v193, v[16:17]
	v_mul_f32_e32 v0, v132, v4
	v_mul_f32_e32 v1, v133, v5
	v_mul_f32_e32 v2, v134, v6
	v_mul_f32_e32 v3, v135, v7
	v_cvt_pk_bf16_f32 v4, v0, v1
	v_cvt_pk_bf16_f32 v5, v2, v3
	v_mul_f32_e32 v6, v8, v68
	v_mul_f32_e32 v7, v9, v68
	v_mul_f32_e32 v8, v10, v68
	v_mul_f32_e32 v9, v11, v68
	ds_write_b64 v194, v[4:5]
	v_mul_f32_e32 v0, v136, v6
	v_mul_f32_e32 v1, v137, v7
	v_mul_f32_e32 v2, v138, v8
	v_mul_f32_e32 v3, v139, v9
	v_cvt_pk_bf16_f32 v4, v0, v1
	v_cvt_pk_bf16_f32 v5, v2, v3
	v_lshl_add_u64 v[6:7], s[62:63], 0, v[154:155]
	v_lshl_add_u64 v[32:33], v[6:7], 0, v[156:157]
	v_lshl_add_u64 v[34:35], v[6:7], 0, v[158:159]
	v_lshl_add_u64 v[36:37], v[6:7], 0, v[160:161]
	v_lshl_add_u64 v[38:39], v[6:7], 0, v[162:163]
	v_lshl_add_u64 v[40:41], v[6:7], 0, v[164:165]
	v_lshl_add_u64 v[42:43], v[6:7], 0, v[166:167]
	v_lshl_add_u64 v[44:45], v[6:7], 0, v[168:169]
	v_lshl_add_u64 v[46:47], v[6:7], 0, v[170:171]
	v_mul_f32_e32 v6, v12, v68
	v_mul_f32_e32 v7, v13, v68
	v_mul_f32_e32 v8, v14, v68
	v_mul_f32_e32 v9, v15, v68
	ds_write_b64 v195, v[4:5]
	v_mul_f32_e32 v0, v140, v6
	v_mul_f32_e32 v1, v141, v7
	v_mul_f32_e32 v2, v142, v8
	v_mul_f32_e32 v3, v143, v9
	v_cvt_pk_bf16_f32 v0, v0, v1
	v_cvt_pk_bf16_f32 v1, v2, v3
	ds_write_b64 v196, v[0:1]
	s_waitcnt lgkmcnt(0)
	ds_read_b128 v[0:3], v197
	ds_read_b128 v[4:7], v197 offset:1088
	ds_read_b128 v[8:11], v197 offset:2176
	ds_read_b128 v[12:15], v197 offset:3264
	ds_read_b128 v[16:19], v197 offset:4352
	ds_read_b128 v[20:23], v197 offset:5440
	ds_read_b128 v[24:27], v197 offset:6528
	ds_read_b128 v[28:31], v197 offset:7616
	s_waitcnt lgkmcnt(7)
	global_store_dwordx4 v[32:33], v[0:3], off offset:2048
	s_waitcnt lgkmcnt(6)
	global_store_dwordx4 v[34:35], v[4:7], off offset:2048
	s_waitcnt lgkmcnt(5)
	global_store_dwordx4 v[36:37], v[8:11], off offset:2048
	s_waitcnt lgkmcnt(4)
	global_store_dwordx4 v[38:39], v[12:15], off offset:2048
	s_waitcnt lgkmcnt(3)
	global_store_dwordx4 v[40:41], v[16:19], off offset:2048
	s_waitcnt lgkmcnt(2)
	global_store_dwordx4 v[42:43], v[20:23], off offset:2048
	s_waitcnt lgkmcnt(1)
	global_store_dwordx4 v[44:45], v[24:27], off offset:2048
	s_waitcnt lgkmcnt(0)
	global_store_dwordx4 v[46:47], v[28:31], off offset:2048
	s_waitcnt lgkmcnt(0)
	s_cbranch_scc0 .LBB0_566
; __device__ __forceinline__ void sb_task(ATT_LAS unsigned char* wl  , int b, int h, int qb, const bf16_t* __restrict__ SQ, const bf16_t* __restrict__ SK, const bf16_t* __restrict__ VT, const float* __restrict__ gout, bf16_t* __restrict__ MIXED) {
;     ...
;     for (int s = 0; s < 8; ++s) qf[s] = *(const bf16x8*)(SQ + (size_t)(b * 4096 + t0 + r) * 1024 + h * 128 + 16 * s + 8 * hh);
;     f32x16 O[4];
; #pragma unroll
;     for (int e = 0; e < 4; ++e)
; #pragma unroll
;         for (int i = 0; i < 16; ++i) O[e][i] = 0.f;
;     float carry = 0.f;
;     const bf16_t* kbase = SK + (size_t)(b * 8 + h) * 130 * 4096 + lane * 8;
;     const bf16_t* vbase = VT + (size_t)1024 * KTOT + (size_t)(b * 8 + h) * 130 * 4096 + lane * 8;
;     ...
;         bf16x8 kf[8];
; #pragma unroll
;         for (int s = 0; s < 8; ++s) kf[s] = *(const bf16x8*)(kbase + (size_t)jt * 4096 + 512 * s);
;         bf16x8 vf[2][4];
; #pragma unroll
;         for (int s2 = 0; s2 < 2; ++s2)
; #pragma unroll
;             for (int e = 0; e < 4; ++e) vf[s2][e] = *(const bf16x8*)(vbase + (size_t)jt * 4096 + (s2 * 4 + e) * 512);
;         f32x16 S;
; #pragma unroll
;         for (int i = 0; i < 16; ++i) S[i] = 0.f;
; #pragma unroll
;         for (int s = 0; s < 8; ++s) S = __builtin_amdgcn_mfma_f32_32x32x16_bf16(kf[s], qf[s], S, 0, 0, 0);
;         const bool diag = (jt == 2 + qb), first = (jt == 1);
;         float L[16]; unsigned vm = 0u;
; #pragma unroll
;         for (int i = 0; i < 16; ++i) { const int kap = 16 * (i >> 3) + 8 * hh + (i & 7); const bool valid = !(diag && kap >= r) && !(first && kap < 16);
;             const float z = S[i], sp = fmaxf(z, 0.f) + __builtin_amdgcn_logf(1.0f + __builtin_amdgcn_exp2f(-fabsf(z)));
;             L[i] = valid ? -sp : 0.f; vm |= valid ? (1u << i) : 0u; }
;         float T0 = 0.f, T1 = 0.f;
; #pragma unroll
;         for (int i = 0; i < 8; ++i) { T0 += L[i]; T1 += L[8 + i]; }
;         const float U0 = __shfl_xor(T0, 32), U1 = __shfl_xor(T1, 32);
.LBB0_563:
	s_ashr_i32 s65, s0, 10
	s_and_b32 s64, s0, 0x7f
	s_lshl_b32 s58, s64, 5
	s_lshl_b32 s62, s65, 12
	s_or_b32 s62, s58, s62
	v_or_b32_e32 v0, s62, v188
	v_ashrrev_i32_e32 v1, 31, v0
	s_bfe_u32 s63, s0, 0x30007
	v_lshlrev_b64 v[0:1], 11, v[0:1]
	v_lshl_add_u64 v[0:1], s[54:55], 0, v[0:1]
	s_lshl_b32 s58, s63, 8
	s_lshl_b32 s65, s65, 3
	v_lshl_add_u64 v[4:5], v[0:1], 0, s[58:59]
	s_or_b32 s76, s65, s63
	s_lshl_b32 s58, s64, 13
	v_mad_i64_i32 v[0:1], s[66:67], s76, v198, v[146:147]
	s_addk_i32 s58, 0x4000
	v_lshl_add_u64 v[28:29], v[0:1], 0, s[58:59]
	global_load_dwordx4 v[0:3], v[28:29], off
	v_lshl_add_u64 v[32:33], v[4:5], 0, v[172:173]
	global_load_dwordx4 v[80:83], v[32:33], off
	global_load_dwordx4 v[16:19], v[28:29], off offset:1024
	global_load_dwordx4 v[84:87], v[32:33], off offset:32
	global_load_dwordx4 v[20:23], v[28:29], off offset:2048
	global_load_dwordx4 v[88:91], v[32:33], off offset:64
	global_load_dwordx4 v[24:27], v[28:29], off offset:3072
	global_load_dwordx4 v[92:95], v[32:33], off offset:96
	v_add_co_u32_e32 v28, vcc, s1, v28
	s_waitcnt vmcnt(6)
	v_mfma_f32_32x32x16_bf16 v[0:15], v[0:3], v[80:83], 0
	v_addc_co_u32_e32 v29, vcc, 0, v29, vcc
	s_waitcnt vmcnt(4)
	v_mfma_f32_32x32x16_bf16 v[0:15], v[16:19], v[84:87], v[0:15]
	global_load_dwordx4 v[16:19], v[28:29], off
	s_waitcnt vmcnt(3)
	v_mfma_f32_32x32x16_bf16 v[0:15], v[20:23], v[88:91], v[0:15]
	global_load_dwordx4 v[96:99], v[32:33], off offset:128
	global_load_dwordx4 v[20:23], v[28:29], off offset:1024
	s_waitcnt vmcnt(3)
	v_mfma_f32_32x32x16_bf16 v[0:15], v[24:27], v[92:95], v[0:15]
	global_load_dwordx4 v[100:103], v[32:33], off offset:160
	global_load_dwordx4 v[24:27], v[28:29], off offset:2048
	global_load_dwordx4 v[104:107], v[32:33], off offset:192
	s_nop 0
	global_load_dwordx4 v[28:31], v[28:29], off offset:3072
	s_nop 0
	global_load_dwordx4 v[108:111], v[32:33], off offset:224
	s_waitcnt vmcnt(6)
	v_mfma_f32_32x32x16_bf16 v[0:15], v[16:19], v[96:99], v[0:15]
	v_mad_i64_i32 v[16:17], s[66:67], s76, v198, v[150:151]
	v_lshl_add_u64 v[32:33], v[16:17], 0, s[58:59]
	s_waitcnt vmcnt(4)
	v_mfma_f32_32x32x16_bf16 v[0:15], v[20:23], v[100:103], v[0:15]
	s_waitcnt vmcnt(2)
	v_mfma_f32_32x32x16_bf16 v[0:15], v[24:27], v[104:107], v[0:15]
	global_load_dwordx4 v[24:27], v[32:33], off
	global_load_dwordx4 v[20:23], v[32:33], off offset:1024
	global_load_dwordx4 v[16:19], v[32:33], off offset:2048
	global_load_dwordx4 v[64:67], v[32:33], off offset:3072
	v_add_co_u32_e32 v32, vcc, s1, v32
	s_nop 1
	v_addc_co_u32_e32 v33, vcc, 0, v33, vcc
	global_load_dwordx4 v[68:71], v[32:33], off
	global_load_dwordx4 v[72:75], v[32:33], off offset:1024
	global_load_dwordx4 v[76:79], v[32:33], off offset:2048
	global_load_dwordx4 v[112:115], v[32:33], off offset:3072
	s_waitcnt vmcnt(8)
	v_mfma_f32_32x32x16_bf16 v[0:15], v[28:31], v[108:111], v[0:15]
	s_nop 11
	v_exp_f32_e64 v29, -|v0|
	v_exp_f32_e64 v43, -|v6|
	v_exp_f32_e64 v31, -|v1|
	v_exp_f32_e64 v35, -|v2|
	v_exp_f32_e64 v37, -|v3|
	v_exp_f32_e64 v39, -|v4|
	v_exp_f32_e64 v41, -|v5|
	v_exp_f32_e64 v49, -|v9|
	v_exp_f32_e64 v53, -|v11|
	v_exp_f32_e64 v61, -|v15|
	v_exp_f32_e64 v45, -|v7|
	v_exp_f32_e64 v47, -|v8|
	v_add_f32_e32 v29, 1.0, v29
	v_add_f32_e32 v43, 1.0, v43
	v_exp_f32_e64 v51, -|v10|
	v_add_f32_e32 v31, 1.0, v31
	v_add_f32_e32 v35, 1.0, v35
	v_add_f32_e32 v37, 1.0, v37
	v_add_f32_e32 v39, 1.0, v39
	v_add_f32_e32 v41, 1.0, v41
	v_add_f32_e32 v49, 1.0, v49
	v_add_f32_e32 v53, 1.0, v53
	v_add_f32_e32 v61, 1.0, v61
	v_log_f32_e32 v29, v29
	v_log_f32_e32 v43, v43
	v_log_f32_e32 v31, v31
	v_log_f32_e32 v35, v35
	v_log_f32_e32 v37, v37
	v_log_f32_e32 v39, v39
	v_log_f32_e32 v41, v41
	v_log_f32_e32 v49, v49
	v_log_f32_e32 v53, v53
	v_log_f32_e32 v61, v61
	v_max_f32_e32 v28, v0, v0
	v_max_f32_e32 v42, v6, v6
	v_exp_f32_e64 v55, -|v12|
	v_add_f32_e32 v45, 1.0, v45
	v_add_f32_e32 v47, 1.0, v47
	v_max_f32_e32 v30, v1, v1
	v_max_f32_e32 v34, v2, v2
	v_max_f32_e32 v36, v3, v3
	v_max_f32_e32 v38, v4, v4
	v_max_f32_e32 v40, v5, v5
	v_max_f32_e32 v48, v9, v9
	v_max_f32_e32 v52, v11, v11
	v_exp_f32_e64 v57, -|v13|
	v_max_f32_e32 v60, v15, v15
	v_max_f32_e32 v28, 0, v28
	v_max_f32_e32 v42, 0, v42
	v_log_f32_e32 v45, v45
	v_log_f32_e32 v47, v47
	v_exp_f32_e64 v59, -|v14|
	v_max_f32_e32 v30, 0, v30
	v_max_f32_e32 v34, 0, v34
	v_max_f32_e32 v36, 0, v36
	v_max_f32_e32 v38, 0, v38
	v_max_f32_e32 v40, 0, v40
	v_max_f32_e32 v48, 0, v48
	v_max_f32_e32 v52, 0, v52
	v_max_f32_e32 v60, 0, v60
	v_add_f32_e32 v51, 1.0, v51
	v_add_f32_e32 v62, v28, v29
	v_add_f32_e32 v28, v42, v43
	v_max_f32_e32 v44, v7, v7
	v_max_f32_e32 v46, v8, v8
	v_log_f32_e32 v51, v51
	v_add_f32_e32 v30, v30, v31
	v_add_f32_e32 v31, v34, v35
	v_add_f32_e32 v34, v36, v37
	v_add_f32_e32 v35, v38, v39
	v_add_f32_e32 v36, v40, v41
	v_add_f32_e32 v38, v48, v49
	v_add_f32_e32 v40, v52, v53
	v_cndmask_b32_e64 v49, 0, -v28, s[16:17]
	v_add_f32_e32 v28, v60, v61
	v_max_f32_e32 v44, 0, v44
	v_max_f32_e32 v46, 0, v46
	v_add_f32_e32 v55, 1.0, v55
	v_cndmask_b32_e64 v119, 0, -v40, s[26:27]
	v_cndmask_b32_e64 v40, 0, -v28, s[36:37]
	v_sub_f32_e32 v28, 0, v62
	v_max_f32_e32 v50, v10, v10
	v_add_f32_e32 v57, 1.0, v57
	v_log_f32_e32 v55, v55
	v_add_f32_e32 v29, v44, v45
	v_add_f32_e32 v37, v46, v47
	v_cndmask_b32_e64 v44, 0, -v30, s[6:7]
	v_cndmask_b32_e64 v28, 0, v28, s[4:5]
	v_max_f32_e32 v50, 0, v50
	v_add_f32_e32 v59, 1.0, v59
	v_log_f32_e32 v57, v57
	v_cndmask_b32_e64 v45, 0, -v31, s[8:9]
	v_cndmask_b32_e64 v116, 0, -v37, s[20:21]
	v_add_f32_e32 v28, v44, v28
	v_max_f32_e32 v54, v12, v12
	v_log_f32_e32 v59, v59
	v_add_f32_e32 v39, v50, v51
	v_cndmask_b32_e64 v46, 0, -v34, s[10:11]
	v_cndmask_b32_e64 v144, 0, -v29, s[18:19]
	v_cndmask_b32_e64 v117, 0, -v38, s[22:23]
	v_add_f32_e32 v29, 0, v116
	v_add_f32_e32 v28, v45, v28
	v_max_f32_e32 v56, v13, v13
	v_max_f32_e32 v54, 0, v54
	v_cndmask_b32_e64 v47, 0, -v35, s[12:13]
	v_cndmask_b32_e64 v118, 0, -v39, s[24:25]
	v_add_f32_e32 v29, v117, v29
	v_add_f32_e32 v28, v46, v28
	v_max_f32_e32 v58, v14, v14
	v_max_f32_e32 v56, 0, v56
	v_add_f32_e32 v41, v54, v55
	v_cndmask_b32_e64 v48, 0, -v36, s[14:15]
	v_add_f32_e32 v29, v118, v29
	v_add_f32_e32 v28, v47, v28
	v_max_f32_e32 v58, 0, v58
	v_add_f32_e32 v42, v56, v57
	v_cndmask_b32_e64 v37, 0, -v41, s[28:29]
	v_add_f32_e32 v29, v119, v29
	v_add_f32_e32 v28, v48, v28
	v_add_f32_e32 v43, v58, v59
	v_cndmask_b32_e64 v38, 0, -v42, s[30:31]
	v_add_f32_e32 v29, v37, v29
	v_add_f32_e32 v28, v49, v28
	v_cndmask_b32_e64 v39, 0, -v43, s[34:35]
	v_add_f32_e32 v29, v38, v29
	v_add_f32_e32 v121, v144, v28
	v_add_f32_e32 v29, v39, v29
	v_mov_b32_e32 v120, v121
	v_mov_b32_e32 v226, v121
	s_nop 1
	v_permlane32_swap_b32_e32 v120, v226
	v_cndmask_b32_e64 v120, v120, v226, s[98:99]
	v_add_f32_e32 v123, v40, v29
	v_mov_b32_e32 v122, v123
	v_mov_b32_e32 v225, v123
	s_nop 1
	v_permlane32_swap_b32_e32 v122, v225
	v_cndmask_b32_e64 v122, v122, v225, s[98:99]
	v_add_f32_e32 v15, v15, v40
	v_add_f32_e32 v14, v14, v39
	s_waitcnt lgkmcnt(1)
; __device__ __forceinline__ void sb_task(ATT_LAS unsigned char* wl  , int b, int h, int qb, const bf16_t* __restrict__ SQ, const bf16_t* __restrict__ SK, const bf16_t* __restrict__ VT, const float* __restrict__ gout, bf16_t* __restrict__ MIXED) {
;     ...
;         bf16x8 kf[8];
; #pragma unroll
;         for (int s = 0; s < 8; ++s) kf[s] = *(const bf16x8*)(kbase + (size_t)jt * 4096 + 512 * s);
;         bf16x8 vf[2][4];
; #pragma unroll
;         for (int s2 = 0; s2 < 2; ++s2)
; #pragma unroll
;             for (int e = 0; e < 4; ++e) vf[s2][e] = *(const bf16x8*)(vbase + (size_t)jt * 4096 + (s2 * 4 + e) * 512);
;         f32x16 S;
; #pragma unroll
;         for (int i = 0; i < 16; ++i) S[i] = 0.f;
; #pragma unroll
;         for (int s = 0; s < 8; ++s) S = __builtin_amdgcn_mfma_f32_32x32x16_bf16(kf[s], qf[s], S, 0, 0, 0);
;     ...
;         const float U0 = __shfl_xor(T0, 32), U1 = __shfl_xor(T1, 32);
;         float run0 = carry + (hh ? (T1 + U1) : (U0 + T1 + U1)), run1 = carry + (hh ? 0.f : U1);
;         float a[16];
; #pragma unroll
;         for (int j = 7; j >= 0; --j) { a[j] = ((vm >> j) & 1u) ? __builtin_amdgcn_exp2f(S[j] + L[j] + run0) : 0.f; run0 += L[j];
;                                        a[8 + j] = ((vm >> (8 + j)) & 1u) ? __builtin_amdgcn_exp2f(S[8 + j] + L[8 + j] + run1) : 0.f; run1 += L[8 + j]; }
;         carry += (T0 + T1) + (U0 + U1);
;         bf16x8 pf[2];
;         pf[0] = pack_bf8(a[0], a[1], a[2], a[3], a[4], a[5], a[6], a[7]); pf[1] = pack_bf8(a[8], a[9], a[10], a[11], a[12], a[13], a[14], a[15]);
; #pragma unroll
;         for (int s2 = 0; s2 < 2; ++s2)
; #pragma unroll
;             for (int e = 0; e < 4; ++e) O[e] = __builtin_amdgcn_mfma_f32_32x32x16_bf16(vf[s2][e], pf[s2], O[e], 0, 0, 0);
;     ...
;         if (!__any(carry > -160.0f)) break;
	v_add_f32_e32 v28, v123, v120
	v_cndmask_b32_e64 v28, v123, v28, s[50:51]
	s_waitcnt lgkmcnt(0)
	v_add_f32_e32 v29, v28, v122
	v_add_f32_e32 v28, 0, v122
	v_cndmask_b32_e64 v41, 0, v28, s[50:51]
	v_add_f32_e32 v15, v41, v15
	v_exp_f32_e32 v15, v15
	v_mov_b32_e32 v28, v7
	v_pk_add_f32 v[28:29], v[28:29], v[144:145]
	v_add_f32_e32 v6, v6, v49
	v_cndmask_b32_e64 v124, v15, 0, s[38:39]
	v_add_f32_e32 v15, v41, v40
	v_add_f32_e32 v14, v15, v14
	v_exp_f32_e32 v14, v14
	v_add_f32_e32 v7, v28, v29
	v_add_f32_e32 v28, v144, v29
	v_add_f32_e32 v6, v6, v28
	v_add_f32_e32 v28, v49, v28
	v_cndmask_b32_e64 v125, v14, 0, s[40:41]
	v_add_f32_e32 v14, v39, v15
	v_add_f32_e32 v15, v48, v28
	v_sub_f32_e32 v4, v4, v35
	v_add_f32_e32 v4, v4, v15
	v_add_f32_e32 v15, v47, v15
	v_sub_f32_e32 v3, v3, v34
	v_add_f32_e32 v3, v3, v15
	v_add_f32_e32 v15, v46, v15
	v_sub_f32_e32 v2, v2, v31
	v_add_f32_e32 v2, v2, v15
	v_add_f32_e32 v15, v45, v15
	v_sub_f32_e32 v1, v1, v30
	v_add_f32_e32 v1, v1, v15
	v_add_f32_e32 v15, v44, v15
	v_sub_f32_e32 v0, v0, v62
	v_sub_f32_e32 v5, v5, v36
	v_add_f32_e32 v0, v0, v15
	v_add_f32_e32 v5, v5, v28
	v_exp_f32_e32 v4, v4
	v_exp_f32_e32 v2, v2
	v_exp_f32_e32 v1, v1
	v_exp_f32_e32 v0, v0
	v_exp_f32_e32 v5, v5
	v_exp_f32_e32 v3, v3
	v_add_f32_e32 v13, v13, v38
	v_exp_f32_e32 v6, v6
	v_add_f32_e32 v13, v13, v14
	v_add_f32_e32 v14, v38, v14
	v_cndmask_b32_e64 v4, 0, v4, s[12:13]
	v_add_f32_e32 v12, v12, v37
	v_cndmask_b32_e64 v2, 0, v2, s[8:9]
	v_cndmask_b32_e64 v1, 0, v1, s[6:7]
	v_cndmask_b32_e64 v0, 0, v0, s[4:5]
	v_exp_f32_e32 v7, v7
	v_cndmask_b32_e64 v5, 0, v5, s[14:15]
	v_cndmask_b32_e64 v3, 0, v3, s[10:11]
	v_cvt_pk_bf16_f32 v0, v0, v1
	v_cvt_pk_bf16_f32 v1, v2, v3
	v_cvt_pk_bf16_f32 v2, v4, v5
	v_add_f32_e32 v4, v12, v14
	v_exp_f32_e32 v4, v4
	v_cndmask_b32_e64 v6, 0, v6, s[16:17]
	v_cndmask_b32_e64 v7, 0, v7, s[18:19]
	v_cvt_pk_bf16_f32 v3, v6, v7
	v_add_f32_e32 v5, v37, v14
	v_add_f32_e32 v6, v11, v119
	v_add_f32_e32 v6, v6, v5
	v_cndmask_b32_e64 v127, v4, 0, s[44:45]
	v_add_f32_e32 v4, v119, v5
	v_add_f32_e32 v5, v10, v118
	v_add_f32_e32 v5, v5, v4
	v_exp_f32_e32 v13, v13
	v_exp_f32_e32 v6, v6
	v_exp_f32_e32 v119, v5
	v_add_f32_e32 v4, v118, v4
	v_add_f32_e32 v5, v9, v117
	v_add_f32_e32 v5, v5, v4
	v_exp_f32_e32 v118, v5
	v_add_f32_e32 v4, v117, v4
	v_add_f32_e32 v5, v8, v116
	v_add_f32_e32 v4, v5, v4
	s_waitcnt vmcnt(7)
	v_mfma_f32_32x32x16_bf16 v[48:63], v[24:27], v[0:3], 0
	v_cndmask_b32_e64 v126, v13, 0, s[42:43]
	v_cndmask_b32_e64 v128, v6, 0, s[46:47]
	v_exp_f32_e32 v116, v4
	s_waitcnt vmcnt(6)
	v_mfma_f32_32x32x16_bf16 v[32:47], v[20:23], v[0:3], 0
	s_waitcnt vmcnt(5)
	v_mfma_f32_32x32x16_bf16 v[16:31], v[16:19], v[0:3], 0
	s_waitcnt vmcnt(4)
	v_mfma_f32_32x32x16_bf16 v[0:15], v[64:67], v[0:3], 0
	v_cndmask_b32_e64 v64, v119, 0, s[48:49]
	v_cndmask_b32_e64 v65, 0, v118, s[22:23]
	v_cndmask_b32_e64 v66, 0, v116, s[20:21]
	v_cvt_pk_bf16_f32 v116, v66, v65
	v_cvt_pk_bf16_f32 v117, v64, v128
	v_cvt_pk_bf16_f32 v118, v127, v126
	v_cvt_pk_bf16_f32 v119, v125, v124
	v_add_f32_e64 v64, v120, v122
	v_add_f32_e64 v65, v121, v123
	s_waitcnt vmcnt(3)
	v_mfma_f32_32x32x16_bf16 v[48:63], v[68:71], v[116:119], v[48:63]
	v_add_f32_e32 v64, v64, v65
	v_cmp_lt_f32_e32 vcc, s72, v64
	s_waitcnt vmcnt(2)
	v_mfma_f32_32x32x16_bf16 v[32:47], v[72:75], v[116:119], v[32:47]
	s_waitcnt vmcnt(1)
	v_mfma_f32_32x32x16_bf16 v[16:31], v[76:79], v[116:119], v[16:31]
	s_waitcnt vmcnt(0)
	v_mfma_f32_32x32x16_bf16 v[0:15], v[112:115], v[116:119], v[0:15]
	s_cbranch_vccz .LBB0_562
	s_lshr_b32 s66, s0, 7
	s_and_b32 s66, s66, 7
	s_add_i32 s65, s65, s66
	s_and_b32 s58, s71, 0x7f
	s_add_i32 s76, s64, 1
	v_mad_i64_i32 v[174:175], s[64:65], s65, v198, v[148:149]
	s_lshl_b32 s58, s58, 13
	v_add_f32_e32 v144, 0, v64
	s_mov_b64 s[64:65], 0
.LBB0_565:
	v_lshl_add_u64 v[124:125], v[174:175], 0, s[58:59]
	v_add_co_u32_e32 v120, vcc, 0x142e3000, v124
	s_cmp_eq_u32 s58, s64
	s_nop 0
	v_addc_co_u32_e32 v121, vcc, 0, v125, vcc
	global_load_dwordx4 v[64:67], v[120:121], off
	global_load_dwordx4 v[112:115], v[120:121], off offset:1024
	global_load_dwordx4 v[116:119], v[120:121], off offset:2048
	v_add_co_u32_e32 v126, vcc, 0x142e4000, v124
	global_load_dwordx4 v[120:123], v[120:121], off offset:3072
	s_nop 0
	v_addc_co_u32_e32 v127, vcc, 0, v125, vcc
	global_load_dwordx4 v[200:203], v[126:127], off offset:3072
	v_add_co_u32_e32 v128, vcc, 0x183e3000, v124
	s_cselect_b64 s[66:67], -1, 0
	s_nop 0
	v_addc_co_u32_e32 v129, vcc, 0, v125, vcc
	v_lshl_add_u64 v[174:175], v[174:175], 0, s[60:61]
	s_waitcnt vmcnt(4)
	v_mfma_f32_32x32x16_bf16 v[64:79], v[64:67], v[80:83], 0
	s_waitcnt vmcnt(3)
	v_mfma_f32_32x32x16_bf16 v[64:79], v[112:115], v[84:87], v[64:79]
	global_load_dwordx4 v[112:115], v[126:127], off
	s_waitcnt vmcnt(3)
	v_mfma_f32_32x32x16_bf16 v[64:79], v[116:119], v[88:91], v[64:79]
	global_load_dwordx4 v[116:119], v[126:127], off offset:1024
	s_waitcnt vmcnt(3)
	v_mfma_f32_32x32x16_bf16 v[64:79], v[120:123], v[92:95], v[64:79]
	global_load_dwordx4 v[120:123], v[126:127], off offset:2048
	global_load_dwordx4 v[140:143], v[128:129], off
	global_load_dwordx4 v[136:139], v[128:129], off offset:1024
	global_load_dwordx4 v[132:135], v[128:129], off offset:2048
	s_nop 0
	global_load_dwordx4 v[128:131], v[128:129], off offset:3072
	s_waitcnt vmcnt(6)
	v_mfma_f32_32x32x16_bf16 v[64:79], v[112:115], v[96:99], v[64:79]
	v_add_co_u32_e32 v112, vcc, 0x183e4000, v124
	s_nop 1
	v_addc_co_u32_e32 v113, vcc, 0, v125, vcc
	s_waitcnt vmcnt(5)
	v_mfma_f32_32x32x16_bf16 v[64:79], v[116:119], v[100:103], v[64:79]
	s_waitcnt vmcnt(4)
; __device__ __forceinline__ void sb_task(ATT_LAS unsigned char* wl  , int b, int h, int qb, const bf16_t* __restrict__ SQ, const bf16_t* __restrict__ SK, const bf16_t* __restrict__ VT, const float* __restrict__ gout, bf16_t* __restrict__ MIXED) {
;     ...
;         for (int s = 0; s < 8; ++s) S = __builtin_amdgcn_mfma_f32_32x32x16_bf16(kf[s], qf[s], S, 0, 0, 0);
;         const bool diag = (jt == 2 + qb), first = (jt == 1);
;         float L[16]; unsigned vm = 0u;
; #pragma unroll
;         for (int i = 0; i < 16; ++i) { const int kap = 16 * (i >> 3) + 8 * hh + (i & 7); const bool valid = !(diag && kap >= r) && !(first && kap < 16);
;             const float z = S[i], sp = fmaxf(z, 0.f) + __builtin_amdgcn_logf(1.0f + __builtin_amdgcn_exp2f(-fabsf(z)));
;             L[i] = valid ? -sp : 0.f; vm |= valid ? (1u << i) : 0u; }
;         float T0 = 0.f, T1 = 0.f;
; #pragma unroll
;         for (int i = 0; i < 8; ++i) { T0 += L[i]; T1 += L[8 + i]; }
;         const float U0 = __shfl_xor(T0, 32), U1 = __shfl_xor(T1, 32);
;         float run0 = carry + (hh ? (T1 + U1) : (U0 + T1 + U1)), run1 = carry + (hh ? 0.f : U1);
	v_mfma_f32_32x32x16_bf16 v[64:79], v[120:123], v[104:107], v[64:79]
	global_load_dwordx4 v[124:127], v[112:113], off
	global_load_dwordx4 v[120:123], v[112:113], off offset:1024
	global_load_dwordx4 v[116:119], v[112:113], off offset:2048
	s_nop 0
	global_load_dwordx4 v[112:115], v[112:113], off offset:3072
	v_mfma_f32_32x32x16_bf16 v[64:79], v[200:203], v[108:111], v[64:79]
	s_nop 11
	v_exp_f32_e64 v157, -|v64|
	v_exp_f32_e64 v161, -|v65|
	v_exp_f32_e64 v208, -|v69|
	v_exp_f32_e64 v209, -|v70|
	v_exp_f32_e64 v210, -|v71|
	v_exp_f32_e64 v211, -|v72|
	v_exp_f32_e64 v212, -|v73|
	v_exp_f32_e64 v213, -|v74|
	v_exp_f32_e64 v214, -|v75|
	v_exp_f32_e64 v165, -|v66|
	v_exp_f32_e64 v199, -|v68|
	v_exp_f32_e64 v217, -|v77|
	v_exp_f32_e64 v219, -|v78|
	v_exp_f32_e64 v221, -|v79|
	v_exp_f32_e64 v169, -|v67|
	v_exp_f32_e64 v215, -|v76|
	v_add_f32_e32 v157, 1.0, v157
	v_max_f32_e32 v200, v69, v69
	v_max_f32_e32 v201, v70, v70
	v_max_f32_e32 v202, v71, v71
	v_max_f32_e32 v203, v72, v72
	v_max_f32_e32 v204, v73, v73
	v_max_f32_e32 v205, v74, v74
	v_max_f32_e32 v206, v75, v75
	v_max_f32_e32 v207, v76, v76
	v_max_f32_e32 v216, v77, v77
	v_max_f32_e32 v218, v78, v78
	v_max_f32_e32 v220, v79, v79
	v_add_f32_e32 v161, 1.0, v161
	v_add_f32_e32 v208, 1.0, v208
	v_add_f32_e32 v209, 1.0, v209
	v_add_f32_e32 v210, 1.0, v210
	v_add_f32_e32 v211, 1.0, v211
	v_add_f32_e32 v212, 1.0, v212
	v_add_f32_e32 v213, 1.0, v213
	v_add_f32_e32 v214, 1.0, v214
	v_log_f32_e32 v157, v157
	v_max_f32_e32 v222, 0, v200
	v_max_f32_e32 v223, 0, v201
	v_max_f32_e32 v224, 0, v202
	v_max_f32_e32 v200, 0, v203
	v_max_f32_e32 v201, 0, v204
	v_max_f32_e32 v202, 0, v205
	v_max_f32_e32 v203, 0, v206
	v_max_f32_e32 v204, 0, v207
	v_max_f32_e32 v205, 0, v216
	v_max_f32_e32 v206, 0, v218
	v_max_f32_e32 v207, 0, v220
	v_add_f32_e32 v165, 1.0, v165
	v_add_f32_e32 v199, 1.0, v199
	v_add_f32_e32 v216, 1.0, v217
	v_add_f32_e32 v217, 1.0, v219
	v_add_f32_e32 v218, 1.0, v221
	v_log_f32_e32 v161, v161
	v_log_f32_e32 v219, v208
	v_log_f32_e32 v220, v209
	v_log_f32_e32 v221, v210
	v_log_f32_e32 v208, v211
	v_log_f32_e32 v209, v212
	v_log_f32_e32 v210, v213
	v_log_f32_e32 v211, v214
	v_max_f32_e32 v155, v64, v64
	v_add_f32_e32 v169, 1.0, v169
	v_log_f32_e32 v165, v165
	v_log_f32_e32 v199, v199
	v_max_f32_e32 v159, v65, v65
	v_max_f32_e32 v155, 0, v155
	v_add_f32_e32 v215, 1.0, v215
	v_log_f32_e32 v169, v169
	v_max_f32_e32 v163, v66, v66
	v_max_f32_e32 v171, v68, v68
	v_max_f32_e32 v159, 0, v159
	v_log_f32_e32 v212, v215
	v_log_f32_e32 v213, v216
	v_log_f32_e32 v214, v217
	v_log_f32_e32 v215, v218
	v_add_f32_e32 v155, v155, v157
	v_max_f32_e32 v167, v67, v67
	v_max_f32_e32 v163, 0, v163
	v_max_f32_e32 v171, 0, v171
	v_add_f32_e32 v157, v159, v161
	v_pk_add_f32 v[200:201], v[200:201], v[208:209]
	v_pk_add_f32 v[202:203], v[202:203], v[210:211]
	v_sub_f32_e32 v210, 0, v155
	v_max_f32_e32 v167, 0, v167
	v_add_f32_e32 v159, v163, v165
	v_add_f32_e32 v163, v171, v199
	v_cndmask_b32_e64 v171, -v157, 0, s[66:67]
	v_sub_f32_e64 v211, -v200, v201
	v_sub_f32_e32 v155, v64, v155
	v_cndmask_b32_e64 v64, v210, 0, s[66:67]
	v_add_f32_e32 v161, v167, v169
	v_cndmask_b32_e64 v199, -v159, 0, s[66:67]
	v_sub_f32_e32 v157, v65, v157
	v_sub_f32_e32 v65, v211, v202
	v_add_f32_e32 v64, v171, v64
	v_pk_add_f32 v[204:205], v[204:205], v[212:213]
	v_pk_add_f32 v[206:207], v[206:207], v[214:215]
	v_cndmask_b32_e64 v214, -v161, 0, s[66:67]
	v_sub_f32_e32 v65, v65, v203
	v_add_f32_e32 v64, v199, v64
	v_add_f32_e32 v165, v222, v219
	v_cndmask_b32_e64 v215, -v163, 0, s[66:67]
	v_sub_f32_e32 v65, v65, v204
	v_add_f32_e32 v64, v214, v64
	v_add_f32_e32 v167, v223, v220
	v_cndmask_b32_e64 v216, -v165, 0, s[66:67]
	v_sub_f32_e32 v65, v65, v205
	v_add_f32_e32 v64, v215, v64
	v_add_f32_e32 v169, v224, v221
	v_cndmask_b32_e64 v217, -v167, 0, s[66:67]
	v_sub_f32_e32 v65, v65, v206
	v_add_f32_e32 v64, v216, v64
	v_cndmask_b32_e64 v218, -v169, 0, s[66:67]
	v_sub_f32_e32 v211, v65, v207
	v_add_f32_e32 v64, v217, v64
	v_mov_b32_e32 v212, v211
	v_mov_b32_e32 v226, v211
	s_nop 1
	v_permlane32_swap_b32_e32 v212, v226
	v_cndmask_b32_e64 v212, v212, v226, s[98:99]
	v_add_f32_e32 v213, v218, v64
	v_mov_b32_e32 v210, v213
	v_mov_b32_e32 v225, v213
	s_nop 1
	v_permlane32_swap_b32_e32 v210, v225
	v_cndmask_b32_e64 v210, v210, v225, s[98:99]
	v_sub_f32_e32 v79, v79, v207
	v_sub_f32_e32 v67, v67, v161
	s_waitcnt lgkmcnt(1)
; __device__ __forceinline__ void sb_task(ATT_LAS unsigned char* wl  , int b, int h, int qb, const bf16_t* __restrict__ SQ, const bf16_t* __restrict__ SK, const bf16_t* __restrict__ VT, const float* __restrict__ gout, bf16_t* __restrict__ MIXED) {
;     ...
;         const float U0 = __shfl_xor(T0, 32), U1 = __shfl_xor(T1, 32);
;         float run0 = carry + (hh ? (T1 + U1) : (U0 + T1 + U1)), run1 = carry + (hh ? 0.f : U1);
;         float a[16];
; #pragma unroll
;         for (int j = 7; j >= 0; --j) { a[j] = ((vm >> j) & 1u) ? __builtin_amdgcn_exp2f(S[j] + L[j] + run0) : 0.f; run0 += L[j];
;                                        a[8 + j] = ((vm >> (8 + j)) & 1u) ? __builtin_amdgcn_exp2f(S[8 + j] + L[8 + j] + run1) : 0.f; run1 += L[8 + j]; }
;         carry += (T0 + T1) + (U0 + U1);
;         bf16x8 pf[2];
;         pf[0] = pack_bf8(a[0], a[1], a[2], a[3], a[4], a[5], a[6], a[7]); pf[1] = pack_bf8(a[8], a[9], a[10], a[11], a[12], a[13], a[14], a[15]);
; #pragma unroll
;         for (int s2 = 0; s2 < 2; ++s2)
; #pragma unroll
;             for (int e = 0; e < 4; ++e) O[e] = __builtin_amdgcn_mfma_f32_32x32x16_bf16(vf[s2][e], pf[s2], O[e], 0, 0, 0);
;     ...
;         if (!__any(carry > -160.0f)) break;
	v_cndmask_b32_e64 v64, 0, v212, s[50:51]
	v_add_f32_e32 v64, v144, v64
	s_waitcnt lgkmcnt(0)
	v_add_f32_e32 v65, v211, v210
	v_sub_f32_e32 v66, v66, v159
	v_add_f32_e32 v159, v64, v79
	v_mov_b32_e32 v79, v64
	v_cndmask_b32_e64 v161, v211, v65, s[50:51]
	v_pk_add_f32 v[64:65], v[78:79], v[206:207] neg_lo:[0,1] neg_hi:[0,1]
	v_add_f32_e32 v78, v161, v212
	v_sub_f32_e32 v169, v71, v169
	v_sub_f32_e32 v167, v70, v167
	v_pk_mov_b32 v[70:71], v[204:205], v[206:207] op_sel:[1,0]
	v_add_f32_e32 v79, v65, v64
	v_mov_b32_e32 v64, v77
	v_add_f32_e32 v77, v144, v78
	v_pk_add_f32 v[70:71], v[64:65], v[70:71] neg_lo:[0,1] neg_hi:[0,1]
	v_add_f32_e32 v65, v218, v77
	v_sub_f32_e32 v165, v69, v165
	v_add_f32_e32 v64, v169, v77
	v_add_f32_e32 v77, v167, v65
	v_add_f32_e32 v65, v217, v65
	v_sub_f32_e32 v163, v68, v163
	v_exp_f32_e32 v78, v79
	v_exp_f32_e32 v64, v64
	v_exp_f32_e32 v77, v77
	v_add_f32_e32 v79, v165, v65
	v_add_f32_e32 v65, v216, v65
	v_add_f32_e32 v161, v163, v65
	v_add_f32_e32 v65, v215, v65
	v_add_f32_e32 v67, v67, v65
	v_add_f32_e32 v65, v214, v65
	v_add_f32_e32 v66, v66, v65
	v_add_f32_e32 v65, v199, v65
	v_cndmask_b32_e64 v163, v64, 0, s[66:67]
	v_exp_f32_e32 v64, v67
	v_cndmask_b32_e64 v67, v77, 0, s[66:67]
	v_add_f32_e32 v77, v157, v65
	v_add_f32_e32 v65, v171, v65
	v_add_f32_e32 v65, v155, v65
	v_exp_f32_e32 v79, v79
	v_exp_f32_e32 v66, v66
	v_exp_f32_e32 v77, v77
	v_exp_f32_e32 v65, v65
	v_exp_f32_e32 v161, v161
	v_cndmask_b32_e64 v79, v79, 0, s[66:67]
	v_cndmask_b32_e64 v157, v64, 0, s[66:67]
	v_cndmask_b32_e64 v66, v66, 0, s[66:67]
	v_cndmask_b32_e64 v64, v77, 0, s[66:67]
	v_cndmask_b32_e64 v65, v65, 0, s[66:67]
	v_add_f32_e32 v70, v70, v71
	v_mov_b32_e32 v77, v71
	v_cndmask_b32_e64 v155, v161, 0, s[66:67]
	v_cvt_pk_bf16_f32 v64, v65, v64
	v_cvt_pk_bf16_f32 v65, v66, v157
	v_cvt_pk_bf16_f32 v66, v155, v79
	v_exp_f32_e32 v79, v70
	v_pk_add_f32 v[70:71], v[76:77], v[204:205] neg_lo:[0,1] neg_hi:[0,1]
	v_pk_mov_b32 v[68:69], v[202:203], v[204:205] op_sel:[1,0]
	v_add_f32_e32 v76, v70, v71
	v_mov_b32_e32 v70, v75
	v_pk_add_f32 v[68:69], v[70:71], v[68:69] neg_lo:[0,1] neg_hi:[0,1]
	v_pk_mov_b32 v[208:209], v[200:201], v[202:203] op_sel:[1,0]
	v_add_f32_e32 v68, v68, v69
	v_mov_b32_e32 v75, v69
	v_exp_f32_e32 v70, v68
	v_pk_add_f32 v[68:69], v[74:75], v[202:203] neg_lo:[0,1] neg_hi:[0,1]
	v_cvt_pk_bf16_f32 v67, v67, v163
	v_exp_f32_e32 v159, v159
	s_waitcnt vmcnt(7)
	v_mfma_f32_32x32x16_bf16 v[48:63], v[140:143], v[64:67], v[48:63]
	v_add_f32_e32 v71, v68, v69
	v_mov_b32_e32 v68, v73
	v_add_f32_e64 v68, v68, -v208
	v_add_f32_e64 v69, v69, -v209
	v_exp_f32_e32 v76, v76
	v_add_f32_e32 v68, v68, v69
	v_mov_b32_e32 v73, v69
	v_exp_f32_e32 v74, v68
	s_waitcnt vmcnt(6)
	v_mfma_f32_32x32x16_bf16 v[32:47], v[136:139], v[64:67], v[32:47]
	v_add_f32_e64 v68, v72, -v200
	v_add_f32_e64 v69, v73, -v201
	v_exp_f32_e32 v71, v71
	v_add_f32_e32 v68, v68, v69
	s_waitcnt vmcnt(5)
	v_mfma_f32_32x32x16_bf16 v[16:31], v[132:135], v[64:67], v[16:31]
	s_waitcnt vmcnt(4)
	v_mfma_f32_32x32x16_bf16 v[0:15], v[128:131], v[64:67], v[0:15]
	v_exp_f32_e32 v64, v68
	v_pk_add_f32 v[68:69], v[210:211], v[212:213]
	v_cvt_pk_bf16_f32 v64, v64, v74
	v_cvt_pk_bf16_f32 v65, v71, v70
	v_cvt_pk_bf16_f32 v66, v76, v79
	v_cvt_pk_bf16_f32 v67, v78, v159
	s_nop 0
	v_add_f32_e32 v68, v68, v69
	v_add_f32_e32 v144, v144, v68
	s_waitcnt vmcnt(3)
	v_mfma_f32_32x32x16_bf16 v[48:63], v[124:127], v[64:67], v[48:63]
	v_cmp_lt_f32_e32 vcc, s72, v144
	s_cmp_lg_u64 vcc, 0
	s_cselect_b64 s[66:67], -1, 0
	s_add_i32 s77, s76, -1
	s_cmp_gt_u32 s76, 1
	s_cselect_b64 s[78:79], -1, 0
	s_and_b64 s[66:67], s[66:67], s[78:79]
	s_waitcnt vmcnt(2)
	v_mfma_f32_32x32x16_bf16 v[32:47], v[120:123], v[64:67], v[32:47]
	s_add_u32 s64, s64, 0x2000
	s_mov_b32 s76, s77
	s_addc_u32 s65, s65, 0
	s_and_b64 vcc, exec, s[66:67]
	s_waitcnt vmcnt(1)
	v_mfma_f32_32x32x16_bf16 v[16:31], v[116:119], v[64:67], v[16:31]
	s_waitcnt vmcnt(0)
	v_mfma_f32_32x32x16_bf16 v[0:15], v[112:115], v[64:67], v[0:15]
	s_cbranch_vccnz .LBB0_565
	s_branch .LBB0_562
